# placement test: one extra s_nop before the younger half's MFMA segment
# speedup vs baseline: 1.0158x; 1.0043x over previous
.Lmla_norescale_B:
	v_exp_f32_e32 v64, v64
	v_exp_f32_e32 v65, v65
	v_exp_f32_e32 v66, v66
	v_exp_f32_e32 v67, v67
	v_exp_f32_e32 v68, v68
	v_exp_f32_e32 v69, v69
	v_exp_f32_e32 v70, v70
	v_exp_f32_e32 v71, v71
	v_cvt_pk_bf16_f32 v234, v64, v65
	v_cvt_pk_bf16_f32 v235, v66, v67
	v_cvt_pk_bf16_f32 v236, v68, v69
	v_cvt_pk_bf16_f32 v237, v70, v71
	v_exp_f32_e32 v72, v72
	v_exp_f32_e32 v73, v73
	v_exp_f32_e32 v74, v74
	v_exp_f32_e32 v75, v75
	v_exp_f32_e32 v76, v76
	v_exp_f32_e32 v77, v77
	v_exp_f32_e32 v78, v78
	v_exp_f32_e32 v79, v79
	v_cvt_pk_bf16_f32 v238, v72, v73
	v_cvt_pk_bf16_f32 v239, v74, v75
	v_cvt_pk_bf16_f32 v240, v76, v77
	v_cvt_pk_bf16_f32 v241, v78, v79
	v_exp_f32_e32 v48, v48
	v_exp_f32_e32 v49, v49
	v_exp_f32_e32 v50, v50
	v_exp_f32_e32 v51, v51
	v_exp_f32_e32 v52, v52
	v_exp_f32_e32 v53, v53
	v_exp_f32_e32 v54, v54
	v_exp_f32_e32 v55, v55
	v_cvt_pk_bf16_f32 v242, v48, v49
	v_cvt_pk_bf16_f32 v243, v50, v51
	v_cvt_pk_bf16_f32 v244, v52, v53
	v_cvt_pk_bf16_f32 v245, v54, v55
	v_exp_f32_e32 v56, v56
	v_exp_f32_e32 v57, v57
	v_exp_f32_e32 v58, v58
	v_exp_f32_e32 v59, v59
	v_exp_f32_e32 v60, v60
	v_exp_f32_e32 v61, v61
	v_exp_f32_e32 v62, v62
	v_exp_f32_e32 v63, v63
	v_cvt_pk_bf16_f32 v246, v56, v57
	v_cvt_pk_bf16_f32 v247, v58, v59
	v_cvt_pk_bf16_f32 v248, v60, v61
	v_cvt_pk_bf16_f32 v249, v62, v63
	v_add_f32_e32 v172, v64, v65
	v_add_f32_e32 v173, v66, v67
	v_add_f32_e32 v177, v68, v69
	v_add_f32_e32 v64, v70, v71
	v_add_f32_e32 v172, v172, v72
	v_add_f32_e32 v173, v173, v73
	v_add_f32_e32 v177, v177, v74
	v_add_f32_e32 v64, v64, v75
	v_add_f32_e32 v172, v172, v76
	v_add_f32_e32 v173, v173, v77
	v_add_f32_e32 v177, v177, v78
	v_add_f32_e32 v64, v64, v79
	v_add_f32_e32 v172, v172, v48
	v_add_f32_e32 v173, v173, v49
	v_add_f32_e32 v177, v177, v50
	v_add_f32_e32 v64, v64, v51
	v_add_f32_e32 v172, v172, v52
	v_add_f32_e32 v173, v173, v53
	v_add_f32_e32 v177, v177, v54
	v_add_f32_e32 v64, v64, v55
	v_add_f32_e32 v172, v172, v56
	v_add_f32_e32 v173, v173, v57
	v_add_f32_e32 v177, v177, v58
	v_add_f32_e32 v64, v64, v59
	v_add_f32_e32 v172, v172, v60
	v_add_f32_e32 v173, v173, v61
	v_add_f32_e32 v177, v177, v62
	v_add_f32_e32 v64, v64, v63
	v_add_f32_e32 v172, v172, v173
	v_add_f32_e32 v177, v177, v64
	v_add_f32_e32 v172, v172, v177
	v_add_f32_e32 v157, v157, v172
	s_mov_b32 s14, 0x41000000
	s_mov_b32 s15, 0
	s_nop 0
	s_and_b32 s12, s28, 1
	s_mul_i32 s13, s12, 0x3400
	v_add_u32_e32 v52, s13, v112
	ds_read_b128 v[48:51], v52
	ds_read_b128 v[122:125], v52 offset:6656
	ds_read_b128 v[118:121], v52 offset:32
	ds_read_b128 v[126:129], v52 offset:6688
	ds_read_b128 v[130:133], v52 offset:64
	ds_read_b128 v[138:141], v52 offset:6720
	ds_read_b128 v[134:137], v52 offset:96
	ds_read_b128 v[142:145], v52 offset:6752
	ds_read_b128 v[146:149], v52 offset:128
	ds_read_b128 v[194:197], v52 offset:6784
	ds_read_b128 v[178:181], v52 offset:160
	ds_read_b128 v[198:201], v52 offset:6816
	s_mul_i32 s13, s12, 0x2400
	v_add_u32_e32 v177, s13, v176
	s_setprio 3
	v_mfma_f32_32x32x16_bf16 v[16:31], v[202:205], v[234:237], v[16:31]
	v_mfma_f32_32x32x16_bf16 v[0:15], v[218:221], v[234:237], v[0:15]
	v_mfma_f32_32x32x16_bf16 v[16:31], v[206:209], v[238:241], v[16:31]
	v_mfma_f32_32x32x16_bf16 v[0:15], v[222:225], v[238:241], v[0:15]
	v_mfma_f32_32x32x16_bf16 v[16:31], v[210:213], v[242:245], v[16:31]
	v_mfma_f32_32x32x16_bf16 v[0:15], v[226:229], v[242:245], v[0:15]
	v_mfma_f32_32x32x16_bf16 v[16:31], v[214:217], v[246:249], v[16:31]
	v_mfma_f32_32x32x16_bf16 v[0:15], v[230:233], v[246:249], v[0:15]
	s_waitcnt lgkmcnt(11)
	v_mfma_f32_32x32x16_bf16 v[64:79], v[48:51], v[80:83], v[32:47]
	s_waitcnt lgkmcnt(10)
	v_mfma_f32_32x32x16_bf16 v[48:63], v[122:125], v[80:83], v[32:47]
	s_waitcnt lgkmcnt(9)
	v_mfma_f32_32x32x16_bf16 v[64:79], v[118:121], v[84:87], v[64:79]
	s_waitcnt lgkmcnt(8)
	v_mfma_f32_32x32x16_bf16 v[48:63], v[126:129], v[84:87], v[48:63]
	s_waitcnt lgkmcnt(7)
	v_mfma_f32_32x32x16_bf16 v[64:79], v[130:133], v[88:91], v[64:79]
	s_waitcnt lgkmcnt(6)
	v_mfma_f32_32x32x16_bf16 v[48:63], v[138:141], v[88:91], v[48:63]
	s_waitcnt lgkmcnt(5)
	v_mfma_f32_32x32x16_bf16 v[64:79], v[134:137], v[92:95], v[64:79]
	s_waitcnt lgkmcnt(4)
	v_mfma_f32_32x32x16_bf16 v[48:63], v[142:145], v[92:95], v[48:63]
	s_waitcnt lgkmcnt(3)
	v_mfma_f32_32x32x16_bf16 v[64:79], v[146:149], v[96:99], v[64:79]
	ds_read_b128 v[202:205], v177 offset:26624
	ds_read_b128 v[206:209], v177 offset:26656
	ds_read_b128 v[218:221], v177 offset:31232
	ds_read_b128 v[222:225], v177 offset:31264
	ds_read_b128 v[210:213], v177 offset:26688
	ds_read_b128 v[214:217], v177 offset:26720
	ds_read_b128 v[226:229], v177 offset:31296
	ds_read_b128 v[230:233], v177 offset:31328
	s_waitcnt lgkmcnt(10)
	v_mfma_f32_32x32x16_bf16 v[48:63], v[194:197], v[96:99], v[48:63]
	s_add_i32 s12, s28, 1
	s_cmp_ge_i32 s12, s22
	s_cbranch_scc1 .Lmla_nowrite_B
	s_and_b32 s12, s12, 1
	s_mul_i32 s13, s12, 0x3400
	v_add3_u32 v172, s13, v165, v166
	s_waitcnt vmcnt(0)
	ds_write_b128 v172, v[104:107]
	s_mulk_i32 s12, 0x2400
	v_add_u32_e32 v172, s12, v169
	v_add_u32_e32 v172, 0x6800, v172
	ds_write2_b64 v172, v[114:115], v[116:117] offset1:2
	s_add_i32 s12, s28, 2
	s_cmp_ge_i32 s12, s22
	s_cbranch_scc1 .Lmla_nowrite_B
	s_nop 1
	global_load_dwordx4 v[104:107], v[150:151], off
	global_load_dwordx4 v[114:117], v[152:153], off
	v_lshl_add_u64 v[150:151], v[150:151], 0, s[26:27]
	v_lshl_add_u64 v[152:153], v[152:153], 0, s[30:31]
